# final rmsnorm pass reads x3 with the nt hint (dead after the read) so the output writes evict already-read lines first
# speedup vs baseline: 1.0004x; 1.0004x over previous
; #define KIN(i) (*(const float* const __attribute__((address_space(4)))*)(kp + 8 * (i)))
; __global__ void __launch_bounds__(NTHREADS, 2) fwd_megakernel(Args args) {
;     ...
;         PH_PROLOG
;         const float* ss3 = SS + 3 * T; const f32x4* gf = (const f32x4*)KIN(19);
;         f32x4* X4 = (f32x4*)X;
;         for (int row = gw; row < T; row += NGW) {
;             f32x4* xr = X4 + (size_t)row * (D / 4) + lane;
;             const float r = __builtin_amdgcn_rsqf(ss3[row] * (1.0f / D) + EPS);
;             f32x4 v[8];
; #pragma unroll
;             for (int j = 0; j < 8; ++j) v[j] = xr[64 * j];
; #pragma unroll
;             for (int j = 0; j < 8; ++j) xr[64 * j] = v[j] * r * gf[lane + 64 * j];
;         }
.LBB0_1505:
	global_load_dwordx4 v[32:35], v[2:3], off
	global_load_dwordx4 v[36:39], v[2:3], off offset:1024
	global_load_dwordx4 v[40:43], v[2:3], off offset:2048
	global_load_dwordx4 v[44:47], v[2:3], off offset:3072
	global_load_dwordx4 v[48:51], v[4:5], off
	global_load_dwordx4 v[52:55], v[6:7], off
	global_load_dwordx4 v[56:59], v[8:9], off
	global_load_dwordx4 v[60:63], v[10:11], off
	v_add_co_u32_e32 v14, vcc, 0xfffff400, v12
	s_nop 1
	v_addc_co_u32_e32 v15, vcc, -1, v13, vcc
	global_load_dword v28, v1, s[0:1]
	s_add_u32 s0, s0, s2
	s_addc_u32 s1, s1, s3
	global_load_dwordx4 v[64:67], v[14:15], off offset:-4096 nt
	global_load_dwordx4 v[68:71], v[14:15], off offset:-3072 nt
	global_load_dwordx4 v[72:75], v[14:15], off offset:-2048 nt
	global_load_dwordx4 v[76:79], v[14:15], off offset:-1024 nt
	global_load_dwordx4 v[80:83], v[14:15], off offset:0 nt
	global_load_dwordx4 v[84:87], v[14:15], off offset:1024 nt
	global_load_dwordx4 v[88:91], v[14:15], off offset:2048 nt
	global_load_dwordx4 v[92:95], v[14:15], off offset:3072 nt
	s_add_i32 s6, s6, s24
	s_cmpk_gt_i32 s6, 0x47ff
	s_cbranch_scc1 .Lp8_tail_a
	v_lshl_add_u64 v[16:17], v[14:15], 0, s[4:5]
	global_load_dword v30, v1, s[0:1]
	s_add_u32 s0, s0, s2
	s_addc_u32 s1, s1, s3
	global_load_dwordx4 v[96:99], v[16:17], off offset:-4096 nt
	global_load_dwordx4 v[100:103], v[16:17], off offset:-3072 nt
	global_load_dwordx4 v[104:107], v[16:17], off offset:-2048 nt
	global_load_dwordx4 v[108:111], v[16:17], off offset:-1024 nt
	global_load_dwordx4 v[112:115], v[16:17], off offset:0 nt
	global_load_dwordx4 v[116:119], v[16:17], off offset:1024 nt
	global_load_dwordx4 v[120:123], v[16:17], off offset:2048 nt
	global_load_dwordx4 v[124:127], v[16:17], off offset:3072 nt
	s_waitcnt vmcnt(9)
	v_fmamk_f32 v28, v28, 0x3a000000, v0
	v_rsq_f32_e32 v28, v28
	s_nop 0
	v_mul_f32_e32 v64, v28, v64
	v_mul_f32_e32 v65, v28, v65
	v_mul_f32_e32 v66, v28, v66
	v_mul_f32_e32 v67, v28, v67
	v_mul_f32_e32 v64, v64, v32
	v_mul_f32_e32 v65, v65, v33
	v_mul_f32_e32 v66, v66, v34
	v_mul_f32_e32 v67, v67, v35
	global_store_dwordx4 v[14:15], v[64:67], off offset:-4096
	v_mul_f32_e32 v68, v28, v68
	v_mul_f32_e32 v69, v28, v69
	v_mul_f32_e32 v70, v28, v70
	v_mul_f32_e32 v71, v28, v71
	v_mul_f32_e32 v68, v68, v36
	v_mul_f32_e32 v69, v69, v37
	v_mul_f32_e32 v70, v70, v38
	v_mul_f32_e32 v71, v71, v39
	global_store_dwordx4 v[14:15], v[68:71], off offset:-3072
	v_mul_f32_e32 v72, v28, v72
	v_mul_f32_e32 v73, v28, v73
	v_mul_f32_e32 v74, v28, v74
	v_mul_f32_e32 v75, v28, v75
	v_mul_f32_e32 v72, v72, v40
	v_mul_f32_e32 v73, v73, v41
	v_mul_f32_e32 v74, v74, v42
	v_mul_f32_e32 v75, v75, v43
	global_store_dwordx4 v[14:15], v[72:75], off offset:-2048
	v_mul_f32_e32 v76, v28, v76
	v_mul_f32_e32 v77, v28, v77
	v_mul_f32_e32 v78, v28, v78
	v_mul_f32_e32 v79, v28, v79
	v_mul_f32_e32 v76, v76, v44
	v_mul_f32_e32 v77, v77, v45
	v_mul_f32_e32 v78, v78, v46
	v_mul_f32_e32 v79, v79, v47
	global_store_dwordx4 v[14:15], v[76:79], off offset:-1024
	v_mul_f32_e32 v80, v28, v80
	v_mul_f32_e32 v81, v28, v81
	v_mul_f32_e32 v82, v28, v82
	v_mul_f32_e32 v83, v28, v83
	v_mul_f32_e32 v80, v80, v48
	v_mul_f32_e32 v81, v81, v49
	v_mul_f32_e32 v82, v82, v50
	v_mul_f32_e32 v83, v83, v51
	global_store_dwordx4 v[14:15], v[80:83], off offset:0
	v_mul_f32_e32 v84, v28, v84
	v_mul_f32_e32 v85, v28, v85
	v_mul_f32_e32 v86, v28, v86
	v_mul_f32_e32 v87, v28, v87
	v_mul_f32_e32 v84, v84, v52
	v_mul_f32_e32 v85, v85, v53
	v_mul_f32_e32 v86, v86, v54
	v_mul_f32_e32 v87, v87, v55
	global_store_dwordx4 v[14:15], v[84:87], off offset:1024
	v_mul_f32_e32 v88, v28, v88
	v_mul_f32_e32 v89, v28, v89
	v_mul_f32_e32 v90, v28, v90
	v_mul_f32_e32 v91, v28, v91
	v_mul_f32_e32 v88, v88, v56
	v_mul_f32_e32 v89, v89, v57
	v_mul_f32_e32 v90, v90, v58
	v_mul_f32_e32 v91, v91, v59
	global_store_dwordx4 v[14:15], v[88:91], off offset:2048
	v_mul_f32_e32 v92, v28, v92
	v_mul_f32_e32 v93, v28, v93
	v_mul_f32_e32 v94, v28, v94
	v_mul_f32_e32 v95, v28, v95
	v_mul_f32_e32 v92, v92, v60
	v_mul_f32_e32 v93, v93, v61
	v_mul_f32_e32 v94, v94, v62
	v_mul_f32_e32 v95, v95, v63
	global_store_dwordx4 v[14:15], v[92:95], off offset:3072
; __global__ void __launch_bounds__(NTHREADS, 2) fwd_megakernel(Args args) {
;     ...
;         for (int row = gw; row < T; row += NGW) {
;             f32x4* xr = X4 + (size_t)row * (D / 4) + lane;
;             const float r = __builtin_amdgcn_rsqf(ss3[row] * (1.0f / D) + EPS);
;             f32x4 v[8];
; #pragma unroll
;             for (int j = 0; j < 8; ++j) v[j] = xr[64 * j];
; #pragma unroll
;             for (int j = 0; j < 8; ++j) xr[64 * j] = v[j] * r * gf[lane + 64 * j];
;         }
.Lp8_loop:
	s_add_i32 s6, s6, s24
	s_cmpk_gt_i32 s6, 0x47ff
	s_cbranch_scc1 .Lp8_tail_b
	v_lshl_add_u64 v[14:15], v[16:17], 0, s[4:5]
	global_load_dword v28, v1, s[0:1]
	s_add_u32 s0, s0, s2
	s_addc_u32 s1, s1, s3
	global_load_dwordx4 v[64:67], v[14:15], off offset:-4096 nt
	global_load_dwordx4 v[68:71], v[14:15], off offset:-3072 nt
	global_load_dwordx4 v[72:75], v[14:15], off offset:-2048 nt
	global_load_dwordx4 v[76:79], v[14:15], off offset:-1024 nt
	global_load_dwordx4 v[80:83], v[14:15], off offset:0 nt
	global_load_dwordx4 v[84:87], v[14:15], off offset:1024 nt
	global_load_dwordx4 v[88:91], v[14:15], off offset:2048 nt
	global_load_dwordx4 v[92:95], v[14:15], off offset:3072 nt
	s_waitcnt vmcnt(17)
	v_fmamk_f32 v30, v30, 0x3a000000, v0
	v_rsq_f32_e32 v30, v30
	s_nop 0
	v_mul_f32_e32 v96, v30, v96
	v_mul_f32_e32 v97, v30, v97
	v_mul_f32_e32 v98, v30, v98
	v_mul_f32_e32 v99, v30, v99
	v_mul_f32_e32 v96, v96, v32
	v_mul_f32_e32 v97, v97, v33
	v_mul_f32_e32 v98, v98, v34
	v_mul_f32_e32 v99, v99, v35
	global_store_dwordx4 v[16:17], v[96:99], off offset:-4096
	v_mul_f32_e32 v100, v30, v100
	v_mul_f32_e32 v101, v30, v101
	v_mul_f32_e32 v102, v30, v102
	v_mul_f32_e32 v103, v30, v103
	v_mul_f32_e32 v100, v100, v36
	v_mul_f32_e32 v101, v101, v37
	v_mul_f32_e32 v102, v102, v38
	v_mul_f32_e32 v103, v103, v39
	global_store_dwordx4 v[16:17], v[100:103], off offset:-3072
	v_mul_f32_e32 v104, v30, v104
	v_mul_f32_e32 v105, v30, v105
	v_mul_f32_e32 v106, v30, v106
	v_mul_f32_e32 v107, v30, v107
	v_mul_f32_e32 v104, v104, v40
	v_mul_f32_e32 v105, v105, v41
	v_mul_f32_e32 v106, v106, v42
	v_mul_f32_e32 v107, v107, v43
	global_store_dwordx4 v[16:17], v[104:107], off offset:-2048
	v_mul_f32_e32 v108, v30, v108
	v_mul_f32_e32 v109, v30, v109
	v_mul_f32_e32 v110, v30, v110
	v_mul_f32_e32 v111, v30, v111
	v_mul_f32_e32 v108, v108, v44
	v_mul_f32_e32 v109, v109, v45
	v_mul_f32_e32 v110, v110, v46
	v_mul_f32_e32 v111, v111, v47
	global_store_dwordx4 v[16:17], v[108:111], off offset:-1024
	v_mul_f32_e32 v112, v30, v112
	v_mul_f32_e32 v113, v30, v113
	v_mul_f32_e32 v114, v30, v114
	v_mul_f32_e32 v115, v30, v115
	v_mul_f32_e32 v112, v112, v48
	v_mul_f32_e32 v113, v113, v49
	v_mul_f32_e32 v114, v114, v50
	v_mul_f32_e32 v115, v115, v51
	global_store_dwordx4 v[16:17], v[112:115], off offset:0
	v_mul_f32_e32 v116, v30, v116
	v_mul_f32_e32 v117, v30, v117
	v_mul_f32_e32 v118, v30, v118
	v_mul_f32_e32 v119, v30, v119
	v_mul_f32_e32 v116, v116, v52
	v_mul_f32_e32 v117, v117, v53
	v_mul_f32_e32 v118, v118, v54
	v_mul_f32_e32 v119, v119, v55
	global_store_dwordx4 v[16:17], v[116:119], off offset:1024
	v_mul_f32_e32 v120, v30, v120
	v_mul_f32_e32 v121, v30, v121
	v_mul_f32_e32 v122, v30, v122
	v_mul_f32_e32 v123, v30, v123
	v_mul_f32_e32 v120, v120, v56
	v_mul_f32_e32 v121, v121, v57
	v_mul_f32_e32 v122, v122, v58
	v_mul_f32_e32 v123, v123, v59
	global_store_dwordx4 v[16:17], v[120:123], off offset:2048
	v_mul_f32_e32 v124, v30, v124
	v_mul_f32_e32 v125, v30, v125
	v_mul_f32_e32 v126, v30, v126
	v_mul_f32_e32 v127, v30, v127
	v_mul_f32_e32 v124, v124, v60
	v_mul_f32_e32 v125, v125, v61
	v_mul_f32_e32 v126, v126, v62
	v_mul_f32_e32 v127, v127, v63
	global_store_dwordx4 v[16:17], v[124:127], off offset:3072
	s_add_i32 s6, s6, s24
	s_cmpk_gt_i32 s6, 0x47ff
	s_cbranch_scc1 .Lp8_tail_a
	v_lshl_add_u64 v[16:17], v[14:15], 0, s[4:5]
	global_load_dword v30, v1, s[0:1]
	s_add_u32 s0, s0, s2
	s_addc_u32 s1, s1, s3
	global_load_dwordx4 v[96:99], v[16:17], off offset:-4096 nt
	global_load_dwordx4 v[100:103], v[16:17], off offset:-3072 nt
	global_load_dwordx4 v[104:107], v[16:17], off offset:-2048 nt
	global_load_dwordx4 v[108:111], v[16:17], off offset:-1024 nt
	global_load_dwordx4 v[112:115], v[16:17], off offset:0 nt
	global_load_dwordx4 v[116:119], v[16:17], off offset:1024 nt
	global_load_dwordx4 v[120:123], v[16:17], off offset:2048 nt
	global_load_dwordx4 v[124:127], v[16:17], off offset:3072 nt
	s_waitcnt vmcnt(17)
	v_fmamk_f32 v28, v28, 0x3a000000, v0
	v_rsq_f32_e32 v28, v28
	s_nop 0
	v_mul_f32_e32 v64, v28, v64
	v_mul_f32_e32 v65, v28, v65
	v_mul_f32_e32 v66, v28, v66
	v_mul_f32_e32 v67, v28, v67
	v_mul_f32_e32 v64, v64, v32
	v_mul_f32_e32 v65, v65, v33
	v_mul_f32_e32 v66, v66, v34
	v_mul_f32_e32 v67, v67, v35
	global_store_dwordx4 v[14:15], v[64:67], off offset:-4096
	v_mul_f32_e32 v68, v28, v68
	v_mul_f32_e32 v69, v28, v69
	v_mul_f32_e32 v70, v28, v70
	v_mul_f32_e32 v71, v28, v71
	v_mul_f32_e32 v68, v68, v36
	v_mul_f32_e32 v69, v69, v37
	v_mul_f32_e32 v70, v70, v38
	v_mul_f32_e32 v71, v71, v39
	global_store_dwordx4 v[14:15], v[68:71], off offset:-3072
	v_mul_f32_e32 v72, v28, v72
	v_mul_f32_e32 v73, v28, v73
	v_mul_f32_e32 v74, v28, v74
	v_mul_f32_e32 v75, v28, v75
	v_mul_f32_e32 v72, v72, v40
	v_mul_f32_e32 v73, v73, v41
	v_mul_f32_e32 v74, v74, v42
	v_mul_f32_e32 v75, v75, v43
	global_store_dwordx4 v[14:15], v[72:75], off offset:-2048
	v_mul_f32_e32 v76, v28, v76
	v_mul_f32_e32 v77, v28, v77
	v_mul_f32_e32 v78, v28, v78
	v_mul_f32_e32 v79, v28, v79
	v_mul_f32_e32 v76, v76, v44
	v_mul_f32_e32 v77, v77, v45
	v_mul_f32_e32 v78, v78, v46
	v_mul_f32_e32 v79, v79, v47
	global_store_dwordx4 v[14:15], v[76:79], off offset:-1024
	v_mul_f32_e32 v80, v28, v80
	v_mul_f32_e32 v81, v28, v81
	v_mul_f32_e32 v82, v28, v82
	v_mul_f32_e32 v83, v28, v83
	v_mul_f32_e32 v80, v80, v48
	v_mul_f32_e32 v81, v81, v49
	v_mul_f32_e32 v82, v82, v50
	v_mul_f32_e32 v83, v83, v51
	global_store_dwordx4 v[14:15], v[80:83], off offset:0
	v_mul_f32_e32 v84, v28, v84
	v_mul_f32_e32 v85, v28, v85
	v_mul_f32_e32 v86, v28, v86
	v_mul_f32_e32 v87, v28, v87
	v_mul_f32_e32 v84, v84, v52
	v_mul_f32_e32 v85, v85, v53
	v_mul_f32_e32 v86, v86, v54
	v_mul_f32_e32 v87, v87, v55
	global_store_dwordx4 v[14:15], v[84:87], off offset:1024
	v_mul_f32_e32 v88, v28, v88
	v_mul_f32_e32 v89, v28, v89
	v_mul_f32_e32 v90, v28, v90
	v_mul_f32_e32 v91, v28, v91
	v_mul_f32_e32 v88, v88, v56
	v_mul_f32_e32 v89, v89, v57
	v_mul_f32_e32 v90, v90, v58
	v_mul_f32_e32 v91, v91, v59
	global_store_dwordx4 v[14:15], v[88:91], off offset:2048
	v_mul_f32_e32 v92, v28, v92
	v_mul_f32_e32 v93, v28, v93
	v_mul_f32_e32 v94, v28, v94
	v_mul_f32_e32 v95, v28, v95
	v_mul_f32_e32 v92, v92, v60
	v_mul_f32_e32 v93, v93, v61
	v_mul_f32_e32 v94, v94, v62
	v_mul_f32_e32 v95, v95, v63
	global_store_dwordx4 v[14:15], v[92:95], off offset:3072
	s_branch .Lp8_loop
